# RG-LRU pass A gate/decay stage regenerated: MFMAs of the next channel group issued ahead of the element-wise work, packed f32 add/mul/fma for token pairs (same operations, bit-identical)
# baseline (speedup 1.0000x reference)
.LBB0_207:
	s_waitcnt lgkmcnt(0)
	ds_read_b128 v[120:123], v180 offset:11008
	s_add_i32 s43, s43, 16
	s_cmpk_lg_i32 s43, 0x80
	s_waitcnt lgkmcnt(0)
	v_lshlrev_b32_e32 v124, 16, v120
	v_and_b32_e32 v125, 0xffff0000, v120
	v_lshlrev_b32_e32 v120, 16, v121
	v_and_b32_e32 v121, 0xffff0000, v121
	v_lshlrev_b32_e32 v126, 16, v122
	v_and_b32_e32 v127, 0xffff0000, v122
	v_lshlrev_b32_e32 v122, 16, v123
	v_and_b32_e32 v123, 0xffff0000, v123
	v_pk_fma_f32 v[128:129], v[6:7], v[120:121], v[22:23]
	v_pk_fma_f32 v[130:131], v[2:3], v[122:123], v[18:19]
	ds_read_b128 v[120:123], v180 offset:11152
	v_pk_fma_f32 v[124:125], v[4:5], v[124:125], v[20:21]
	v_pk_fma_f32 v[126:127], v[0:1], v[126:127], v[16:17]
	s_waitcnt lgkmcnt(0)
	v_lshlrev_b32_e32 v132, 16, v120
	v_and_b32_e32 v133, 0xffff0000, v120
	v_lshlrev_b32_e32 v120, 16, v121
	v_and_b32_e32 v121, 0xffff0000, v121
	v_lshlrev_b32_e32 v134, 16, v122
	v_and_b32_e32 v135, 0xffff0000, v122
	v_lshlrev_b32_e32 v122, 16, v123
	v_and_b32_e32 v123, 0xffff0000, v123
	v_pk_fma_f32 v[128:129], v[14:15], v[120:121], v[128:129]
	v_pk_fma_f32 v[130:131], v[10:11], v[122:123], v[130:131]
	ds_read_b128 v[120:123], v180 offset:11296
	v_pk_fma_f32 v[124:125], v[12:13], v[132:133], v[124:125]
	v_pk_fma_f32 v[126:127], v[8:9], v[134:135], v[126:127]
	s_waitcnt lgkmcnt(0)
	v_lshlrev_b32_e32 v132, 16, v120
	v_and_b32_e32 v133, 0xffff0000, v120
	v_lshlrev_b32_e32 v120, 16, v121
	v_and_b32_e32 v121, 0xffff0000, v121
	v_lshlrev_b32_e32 v134, 16, v122
	v_and_b32_e32 v135, 0xffff0000, v122
	v_lshlrev_b32_e32 v122, 16, v123
	v_and_b32_e32 v123, 0xffff0000, v123
	v_pk_fma_f32 v[124:125], v[24:25], v[132:133], v[124:125]
	v_pk_fma_f32 v[128:129], v[26:27], v[120:121], v[128:129]
	v_pk_fma_f32 v[132:133], v[28:29], v[134:135], v[126:127]
	v_pk_fma_f32 v[126:127], v[30:31], v[122:123], v[130:131]
	ds_read_b128 v[120:123], v180 offset:11440
	s_waitcnt lgkmcnt(0)
	v_lshlrev_b32_e32 v130, 16, v120
	v_and_b32_e32 v131, 0xffff0000, v120
	v_lshlrev_b32_e32 v120, 16, v121
	v_and_b32_e32 v121, 0xffff0000, v121
	v_lshlrev_b32_e32 v134, 16, v122
	v_and_b32_e32 v135, 0xffff0000, v122
	v_lshlrev_b32_e32 v136, 16, v123
	v_and_b32_e32 v137, 0xffff0000, v123
	v_pk_fma_f32 v[122:123], v[34:35], v[120:121], v[128:129]
	v_pk_fma_f32 v[120:121], v[32:33], v[130:131], v[124:125]
	v_pk_fma_f32 v[126:127], v[38:39], v[136:137], v[126:127]
	v_pk_fma_f32 v[124:125], v[36:37], v[134:135], v[132:133]
	ds_write_b128 v179, v[120:123] offset:2304
	ds_write_b128 v179, v[124:127] offset:2320
	v_cvt_pk_bf16_f32 v120, v120, v121
	v_cvt_pk_bf16_f32 v121, v122, v123
	v_cvt_pk_bf16_f32 v122, v124, v125
	v_cvt_pk_bf16_f32 v123, v126, v127
	ds_write_b128 v180, v[120:123]
	ds_read_b128 v[120:123], v180 offset:12160
	s_waitcnt lgkmcnt(0)
	v_lshlrev_b32_e32 v124, 16, v120
	v_and_b32_e32 v125, 0xffff0000, v120
	v_lshlrev_b32_e32 v120, 16, v121
	v_and_b32_e32 v121, 0xffff0000, v121
	v_lshlrev_b32_e32 v126, 16, v122
	v_and_b32_e32 v127, 0xffff0000, v122
	v_lshlrev_b32_e32 v122, 16, v123
	v_and_b32_e32 v123, 0xffff0000, v123
	v_pk_fma_f32 v[128:129], v[6:7], v[120:121], v[22:23]
	v_pk_fma_f32 v[130:131], v[2:3], v[122:123], v[18:19]
	ds_read_b128 v[120:123], v180 offset:12304
	v_pk_fma_f32 v[124:125], v[4:5], v[124:125], v[20:21]
	v_pk_fma_f32 v[126:127], v[0:1], v[126:127], v[16:17]
	s_waitcnt lgkmcnt(0)
	v_lshlrev_b32_e32 v132, 16, v120
	v_and_b32_e32 v133, 0xffff0000, v120
	v_lshlrev_b32_e32 v120, 16, v121
	v_and_b32_e32 v121, 0xffff0000, v121
	v_lshlrev_b32_e32 v134, 16, v122
	v_and_b32_e32 v135, 0xffff0000, v122
	v_lshlrev_b32_e32 v122, 16, v123
	v_and_b32_e32 v123, 0xffff0000, v123
	v_pk_fma_f32 v[128:129], v[14:15], v[120:121], v[128:129]
	v_pk_fma_f32 v[130:131], v[10:11], v[122:123], v[130:131]
	ds_read_b128 v[120:123], v180 offset:12448
	v_pk_fma_f32 v[124:125], v[12:13], v[132:133], v[124:125]
	v_pk_fma_f32 v[126:127], v[8:9], v[134:135], v[126:127]
	s_waitcnt lgkmcnt(0)
	v_lshlrev_b32_e32 v132, 16, v120
	v_and_b32_e32 v133, 0xffff0000, v120
	v_lshlrev_b32_e32 v120, 16, v121
	v_and_b32_e32 v121, 0xffff0000, v121
	v_lshlrev_b32_e32 v134, 16, v122
	v_and_b32_e32 v135, 0xffff0000, v122
	v_lshlrev_b32_e32 v122, 16, v123
	v_and_b32_e32 v123, 0xffff0000, v123
	v_pk_fma_f32 v[124:125], v[24:25], v[132:133], v[124:125]
	v_pk_fma_f32 v[128:129], v[26:27], v[120:121], v[128:129]
	v_pk_fma_f32 v[132:133], v[28:29], v[134:135], v[126:127]
	v_pk_fma_f32 v[126:127], v[30:31], v[122:123], v[130:131]
	ds_read_b128 v[120:123], v180 offset:12592
	s_waitcnt lgkmcnt(0)
	v_lshlrev_b32_e32 v130, 16, v120
	v_and_b32_e32 v131, 0xffff0000, v120
	v_lshlrev_b32_e32 v120, 16, v121
	v_and_b32_e32 v121, 0xffff0000, v121
	v_lshlrev_b32_e32 v134, 16, v122
	v_and_b32_e32 v135, 0xffff0000, v122
	v_lshlrev_b32_e32 v136, 16, v123
	v_and_b32_e32 v137, 0xffff0000, v123
	v_pk_fma_f32 v[122:123], v[34:35], v[120:121], v[128:129]
	v_pk_fma_f32 v[120:121], v[32:33], v[130:131], v[124:125]
	v_pk_fma_f32 v[126:127], v[38:39], v[136:137], v[126:127]
	v_pk_fma_f32 v[124:125], v[36:37], v[134:135], v[132:133]
	ds_write_b128 v179, v[120:123] offset:4480
	ds_write_b128 v179, v[124:127] offset:4496
	v_cvt_pk_bf16_f32 v120, v120, v121
	v_cvt_pk_bf16_f32 v121, v122, v123
	v_cvt_pk_bf16_f32 v122, v124, v125
	v_cvt_pk_bf16_f32 v123, v126, v127
	ds_write_b128 v180, v[120:123] offset:1152
	s_waitcnt lgkmcnt(0)
	s_mov_b32 s0, 0x37d00d01
	s_mov_b32 s1, 0x37d00d01
	s_mov_b32 s80, 0x3ab60b61
	s_mov_b32 s81, 0x3ab60b61
	s_mov_b32 s82, 0x3c088889
	s_mov_b32 s83, 0x3c088889
	s_mov_b32 s84, 0x3d2aaaab
	s_mov_b32 s85, 0x3d2aaaab
	ds_read_b128 v[120:123], v173
	ds_read_b128 v[222:225], v173 offset:64
	v_mov_b32_e32 v168, 1.0
	v_mov_b32_e32 v232, 0xbfb8aa3b
	v_add_u32_e32 v233, 2304, v175
	s_waitcnt lgkmcnt(0)
	v_mfma_f32_16x16x32_bf16 v[128:131], v[120:123], v[40:43], 0
	v_mfma_f32_16x16x32_bf16 v[132:135], v[120:123], v[72:75], 0
	v_mfma_f32_16x16x32_bf16 v[128:131], v[222:225], v[44:47], v[128:131]
	v_mfma_f32_16x16x32_bf16 v[132:135], v[222:225], v[76:79], v[132:135]
	v_mfma_f32_16x16x32_bf16 v[136:139], v[120:123], v[48:51], 0
	v_mfma_f32_16x16x32_bf16 v[140:143], v[120:123], v[80:83], 0
	v_mfma_f32_16x16x32_bf16 v[136:139], v[222:225], v[52:55], v[136:139]
	v_mfma_f32_16x16x32_bf16 v[140:143], v[222:225], v[84:87], v[140:143]
	s_nop 7
	ds_read2_b32 v[230:231], v233 offset0:0 offset1:68
	v_add_f32_e64 v124, v128, v161
	v_add_f32_e64 v125, v129, v161
	v_add_f32_e64 v126, v132, v163
	v_add_f32_e64 v127, v133, v163
	v_pk_mul_f32 v[124:125], v[124:125], v[232:233] op_sel_hi:[1,0]
	v_pk_mul_f32 v[126:127], v[126:127], v[232:233] op_sel_hi:[1,0]
	v_exp_f32_e32 v124, v124
	v_exp_f32_e32 v125, v125
	v_exp_f32_e32 v126, v126
	v_exp_f32_e32 v127, v127
	v_pk_add_f32 v[124:125], v[124:125], v[168:169] op_sel_hi:[1,0]
	v_pk_add_f32 v[126:127], v[126:127], v[168:169] op_sel_hi:[1,0]
	v_rcp_f32_e32 v124, v124
	v_rcp_f32_e32 v125, v125
	v_rcp_f32_e32 v126, v126
	v_rcp_f32_e32 v127, v127
	v_pk_mul_f32 v[170:171], v[124:125], v[98:99] op_sel_hi:[1,0]
	v_mul_f32_e32 v226, 0x3fb8aa3b, v170
	v_mul_f32_e32 v227, 0x3fb8aa3b, v171
	v_pk_add_f32 v[170:171], v[170:171], v[170:171]
	v_exp_f32_e32 v226, v226
	v_exp_f32_e32 v227, v227
	v_pk_fma_f32 v[228:229], v[170:171], s[0:1], v[198:199] op_sel_hi:[1,1,0]
	v_pk_fma_f32 v[228:229], v[170:171], v[228:229], s[80:81]
	v_pk_fma_f32 v[228:229], v[170:171], v[228:229], s[82:83]
	v_pk_fma_f32 v[228:229], v[170:171], v[228:229], s[84:85]
	v_fmaak_f32 v228, v170, v228, 0x3e2aaaab
	v_fmaak_f32 v229, v171, v229, 0x3e2aaaab
	v_fma_f32 v228, v170, v228, 0.5
	v_fma_f32 v229, v171, v229, 0.5
	v_pk_fma_f32 v[228:229], v[170:171], v[228:229], v[168:169] op_sel_hi:[1,1,0]
	v_pk_mul_f32 v[228:229], v[170:171], v[228:229] neg_lo:[0,1] neg_hi:[0,1]
	v_max_f32_e32 v228, 0, v228
	v_max_f32_e32 v229, 0, v229
	v_sqrt_f32_e32 v228, v228
	v_sqrt_f32_e32 v229, v229
	ds_write_b32 v175, v226 offset:6656
	ds_write_b32 v175, v227 offset:6928
	v_pk_mul_f32 v[228:229], v[126:127], v[228:229]
	s_waitcnt lgkmcnt(2)
	v_pk_mul_f32 v[228:229], v[230:231], v[228:229]
	ds_write2_b32 v233, v228, v229 offset0:0 offset1:68
	ds_read2_b32 v[230:231], v233 offset0:136 offset1:204
	v_add_f32_e64 v124, v130, v161
	v_add_f32_e64 v125, v131, v161
	v_add_f32_e64 v126, v134, v163
	v_add_f32_e64 v127, v135, v163
	v_pk_mul_f32 v[124:125], v[124:125], v[232:233] op_sel_hi:[1,0]
	v_pk_mul_f32 v[126:127], v[126:127], v[232:233] op_sel_hi:[1,0]
	v_exp_f32_e32 v124, v124
	v_exp_f32_e32 v125, v125
	v_exp_f32_e32 v126, v126
	v_exp_f32_e32 v127, v127
	v_pk_add_f32 v[124:125], v[124:125], v[168:169] op_sel_hi:[1,0]
	v_pk_add_f32 v[126:127], v[126:127], v[168:169] op_sel_hi:[1,0]
	v_rcp_f32_e32 v124, v124
	v_rcp_f32_e32 v125, v125
	v_rcp_f32_e32 v126, v126
	v_rcp_f32_e32 v127, v127
	v_pk_mul_f32 v[170:171], v[124:125], v[98:99] op_sel_hi:[1,0]
	v_mul_f32_e32 v226, 0x3fb8aa3b, v170
	v_mul_f32_e32 v227, 0x3fb8aa3b, v171
	v_pk_add_f32 v[170:171], v[170:171], v[170:171]
	v_exp_f32_e32 v226, v226
	v_exp_f32_e32 v227, v227
	v_pk_fma_f32 v[228:229], v[170:171], s[0:1], v[198:199] op_sel_hi:[1,1,0]
	v_pk_fma_f32 v[228:229], v[170:171], v[228:229], s[80:81]
	v_pk_fma_f32 v[228:229], v[170:171], v[228:229], s[82:83]
	v_pk_fma_f32 v[228:229], v[170:171], v[228:229], s[84:85]
	v_fmaak_f32 v228, v170, v228, 0x3e2aaaab
	v_fmaak_f32 v229, v171, v229, 0x3e2aaaab
	v_fma_f32 v228, v170, v228, 0.5
	v_fma_f32 v229, v171, v229, 0.5
	v_pk_fma_f32 v[228:229], v[170:171], v[228:229], v[168:169] op_sel_hi:[1,1,0]
	v_pk_mul_f32 v[228:229], v[170:171], v[228:229] neg_lo:[0,1] neg_hi:[0,1]
	v_max_f32_e32 v228, 0, v228
	v_max_f32_e32 v229, 0, v229
	v_sqrt_f32_e32 v228, v228
	v_sqrt_f32_e32 v229, v229
	ds_write_b32 v175, v226 offset:7200
	ds_write_b32 v175, v227 offset:7472
	v_pk_mul_f32 v[228:229], v[126:127], v[228:229]
	s_waitcnt lgkmcnt(2)
	v_pk_mul_f32 v[228:229], v[230:231], v[228:229]
	ds_write2_b32 v233, v228, v229 offset0:136 offset1:204
	v_mfma_f32_16x16x32_bf16 v[128:131], v[120:123], v[56:59], 0
	v_mfma_f32_16x16x32_bf16 v[132:135], v[120:123], v[88:91], 0
	v_mfma_f32_16x16x32_bf16 v[128:131], v[222:225], v[60:63], v[128:131]
	v_mfma_f32_16x16x32_bf16 v[132:135], v[222:225], v[92:95], v[132:135]
	ds_read2_b32 v[230:231], v233 offset0:16 offset1:84
	v_add_f32_e64 v124, v136, v181
	v_add_f32_e64 v125, v137, v181
	v_pk_add_f32 v[126:127], v[140:141], v[188:189] op_sel_hi:[1,0]
	v_pk_mul_f32 v[124:125], v[124:125], v[232:233] op_sel_hi:[1,0]
	v_pk_mul_f32 v[126:127], v[126:127], v[232:233] op_sel_hi:[1,0]
	v_exp_f32_e32 v124, v124
	v_exp_f32_e32 v125, v125
	v_exp_f32_e32 v126, v126
	v_exp_f32_e32 v127, v127
	v_pk_add_f32 v[124:125], v[124:125], v[168:169] op_sel_hi:[1,0]
	v_pk_add_f32 v[126:127], v[126:127], v[168:169] op_sel_hi:[1,0]
	v_rcp_f32_e32 v124, v124
	v_rcp_f32_e32 v125, v125
	v_rcp_f32_e32 v126, v126
	v_rcp_f32_e32 v127, v127
	v_mul_f32_e64 v170, v124, v193
	v_mul_f32_e64 v171, v125, v193
	v_mul_f32_e32 v226, 0x3fb8aa3b, v170
	v_mul_f32_e32 v227, 0x3fb8aa3b, v171
	v_pk_add_f32 v[170:171], v[170:171], v[170:171]
	v_exp_f32_e32 v226, v226
	v_exp_f32_e32 v227, v227
	v_pk_fma_f32 v[228:229], v[170:171], s[0:1], v[198:199] op_sel_hi:[1,1,0]
	v_pk_fma_f32 v[228:229], v[170:171], v[228:229], s[80:81]
	v_pk_fma_f32 v[228:229], v[170:171], v[228:229], s[82:83]
	v_pk_fma_f32 v[228:229], v[170:171], v[228:229], s[84:85]
	v_fmaak_f32 v228, v170, v228, 0x3e2aaaab
	v_fmaak_f32 v229, v171, v229, 0x3e2aaaab
	v_fma_f32 v228, v170, v228, 0.5
	v_fma_f32 v229, v171, v229, 0.5
	v_pk_fma_f32 v[228:229], v[170:171], v[228:229], v[168:169] op_sel_hi:[1,1,0]
	v_pk_mul_f32 v[228:229], v[170:171], v[228:229] neg_lo:[0,1] neg_hi:[0,1]
	v_max_f32_e32 v228, 0, v228
	v_max_f32_e32 v229, 0, v229
	v_sqrt_f32_e32 v228, v228
	v_sqrt_f32_e32 v229, v229
	ds_write_b32 v175, v226 offset:6720
	ds_write_b32 v175, v227 offset:6992
	v_pk_mul_f32 v[228:229], v[126:127], v[228:229]
	s_waitcnt lgkmcnt(2)
	v_pk_mul_f32 v[228:229], v[230:231], v[228:229]
	ds_write2_b32 v233, v228, v229 offset0:16 offset1:84
	ds_read2_b32 v[230:231], v233 offset0:152 offset1:220
	v_add_f32_e64 v124, v138, v181
	v_add_f32_e64 v125, v139, v181
	v_pk_add_f32 v[126:127], v[142:143], v[188:189] op_sel_hi:[1,0]
	v_pk_mul_f32 v[124:125], v[124:125], v[232:233] op_sel_hi:[1,0]
	v_pk_mul_f32 v[126:127], v[126:127], v[232:233] op_sel_hi:[1,0]
	v_exp_f32_e32 v124, v124
	v_exp_f32_e32 v125, v125
	v_exp_f32_e32 v126, v126
	v_exp_f32_e32 v127, v127
	v_pk_add_f32 v[124:125], v[124:125], v[168:169] op_sel_hi:[1,0]
	v_pk_add_f32 v[126:127], v[126:127], v[168:169] op_sel_hi:[1,0]
	v_rcp_f32_e32 v124, v124
	v_rcp_f32_e32 v125, v125
	v_rcp_f32_e32 v126, v126
	v_rcp_f32_e32 v127, v127
	v_mul_f32_e64 v170, v124, v193
	v_mul_f32_e64 v171, v125, v193
	v_mul_f32_e32 v226, 0x3fb8aa3b, v170
	v_mul_f32_e32 v227, 0x3fb8aa3b, v171
	v_pk_add_f32 v[170:171], v[170:171], v[170:171]
	v_exp_f32_e32 v226, v226
	v_exp_f32_e32 v227, v227
	v_pk_fma_f32 v[228:229], v[170:171], s[0:1], v[198:199] op_sel_hi:[1,1,0]
	v_pk_fma_f32 v[228:229], v[170:171], v[228:229], s[80:81]
	v_pk_fma_f32 v[228:229], v[170:171], v[228:229], s[82:83]
	v_pk_fma_f32 v[228:229], v[170:171], v[228:229], s[84:85]
	v_fmaak_f32 v228, v170, v228, 0x3e2aaaab
	v_fmaak_f32 v229, v171, v229, 0x3e2aaaab
	v_fma_f32 v228, v170, v228, 0.5
	v_fma_f32 v229, v171, v229, 0.5
	v_pk_fma_f32 v[228:229], v[170:171], v[228:229], v[168:169] op_sel_hi:[1,1,0]
	v_pk_mul_f32 v[228:229], v[170:171], v[228:229] neg_lo:[0,1] neg_hi:[0,1]
	v_max_f32_e32 v228, 0, v228
	v_max_f32_e32 v229, 0, v229
	v_sqrt_f32_e32 v228, v228
	v_sqrt_f32_e32 v229, v229
	ds_write_b32 v175, v226 offset:7264
	ds_write_b32 v175, v227 offset:7536
	v_pk_mul_f32 v[228:229], v[126:127], v[228:229]
	s_waitcnt lgkmcnt(2)
	v_pk_mul_f32 v[228:229], v[230:231], v[228:229]
	ds_write2_b32 v233, v228, v229 offset0:152 offset1:220
	v_mfma_f32_16x16x32_bf16 v[136:139], v[120:123], v[64:67], 0
	v_mfma_f32_16x16x32_bf16 v[140:143], v[120:123], v[100:103], 0
	v_mfma_f32_16x16x32_bf16 v[136:139], v[222:225], v[68:71], v[136:139]
	v_mfma_f32_16x16x32_bf16 v[140:143], v[222:225], v[104:107], v[140:143]
	ds_read2_b32 v[230:231], v233 offset0:32 offset1:100
	v_add_f32_e64 v124, v128, v189
	v_add_f32_e64 v125, v129, v189
	v_pk_add_f32 v[126:127], v[132:133], v[190:191] op_sel_hi:[1,0]
	v_pk_mul_f32 v[124:125], v[124:125], v[232:233] op_sel_hi:[1,0]
	v_pk_mul_f32 v[126:127], v[126:127], v[232:233] op_sel_hi:[1,0]
	v_exp_f32_e32 v124, v124
	v_exp_f32_e32 v125, v125
	v_exp_f32_e32 v126, v126
	v_exp_f32_e32 v127, v127
	v_pk_add_f32 v[124:125], v[124:125], v[168:169] op_sel_hi:[1,0]
	v_pk_add_f32 v[126:127], v[126:127], v[168:169] op_sel_hi:[1,0]
	v_rcp_f32_e32 v124, v124
	v_rcp_f32_e32 v125, v125
	v_rcp_f32_e32 v126, v126
	v_rcp_f32_e32 v127, v127
	v_pk_mul_f32 v[170:171], v[124:125], v[220:221] op_sel_hi:[1,0]
	v_mul_f32_e32 v226, 0x3fb8aa3b, v170
	v_mul_f32_e32 v227, 0x3fb8aa3b, v171
	v_pk_add_f32 v[170:171], v[170:171], v[170:171]
	v_exp_f32_e32 v226, v226
	v_exp_f32_e32 v227, v227
	v_pk_fma_f32 v[228:229], v[170:171], s[0:1], v[198:199] op_sel_hi:[1,1,0]
	v_pk_fma_f32 v[228:229], v[170:171], v[228:229], s[80:81]
	v_pk_fma_f32 v[228:229], v[170:171], v[228:229], s[82:83]
	v_pk_fma_f32 v[228:229], v[170:171], v[228:229], s[84:85]
	v_fmaak_f32 v228, v170, v228, 0x3e2aaaab
	v_fmaak_f32 v229, v171, v229, 0x3e2aaaab
	v_fma_f32 v228, v170, v228, 0.5
	v_fma_f32 v229, v171, v229, 0.5
	v_pk_fma_f32 v[228:229], v[170:171], v[228:229], v[168:169] op_sel_hi:[1,1,0]
	v_pk_mul_f32 v[228:229], v[170:171], v[228:229] neg_lo:[0,1] neg_hi:[0,1]
	v_max_f32_e32 v228, 0, v228
	v_max_f32_e32 v229, 0, v229
	v_sqrt_f32_e32 v228, v228
	v_sqrt_f32_e32 v229, v229
	ds_write_b32 v175, v226 offset:6784
	ds_write_b32 v175, v227 offset:7056
	v_pk_mul_f32 v[228:229], v[126:127], v[228:229]
	s_waitcnt lgkmcnt(2)
	v_pk_mul_f32 v[228:229], v[230:231], v[228:229]
	ds_write2_b32 v233, v228, v229 offset0:32 offset1:100
	ds_read2_b32 v[230:231], v233 offset0:168 offset1:236
	v_add_f32_e64 v124, v130, v189
	v_add_f32_e64 v125, v131, v189
	v_pk_add_f32 v[126:127], v[134:135], v[190:191] op_sel_hi:[1,0]
	v_pk_mul_f32 v[124:125], v[124:125], v[232:233] op_sel_hi:[1,0]
	v_pk_mul_f32 v[126:127], v[126:127], v[232:233] op_sel_hi:[1,0]
	v_exp_f32_e32 v124, v124
	v_exp_f32_e32 v125, v125
	v_exp_f32_e32 v126, v126
	v_exp_f32_e32 v127, v127
	v_pk_add_f32 v[124:125], v[124:125], v[168:169] op_sel_hi:[1,0]
	v_pk_add_f32 v[126:127], v[126:127], v[168:169] op_sel_hi:[1,0]
	v_rcp_f32_e32 v124, v124
	v_rcp_f32_e32 v125, v125
	v_rcp_f32_e32 v126, v126
	v_rcp_f32_e32 v127, v127
	v_pk_mul_f32 v[170:171], v[124:125], v[220:221] op_sel_hi:[1,0]
	v_mul_f32_e32 v226, 0x3fb8aa3b, v170
	v_mul_f32_e32 v227, 0x3fb8aa3b, v171
	v_pk_add_f32 v[170:171], v[170:171], v[170:171]
	v_exp_f32_e32 v226, v226
	v_exp_f32_e32 v227, v227
	v_pk_fma_f32 v[228:229], v[170:171], s[0:1], v[198:199] op_sel_hi:[1,1,0]
	v_pk_fma_f32 v[228:229], v[170:171], v[228:229], s[80:81]
	v_pk_fma_f32 v[228:229], v[170:171], v[228:229], s[82:83]
	v_pk_fma_f32 v[228:229], v[170:171], v[228:229], s[84:85]
	v_fmaak_f32 v228, v170, v228, 0x3e2aaaab
	v_fmaak_f32 v229, v171, v229, 0x3e2aaaab
	v_fma_f32 v228, v170, v228, 0.5
	v_fma_f32 v229, v171, v229, 0.5
	v_pk_fma_f32 v[228:229], v[170:171], v[228:229], v[168:169] op_sel_hi:[1,1,0]
	v_pk_mul_f32 v[228:229], v[170:171], v[228:229] neg_lo:[0,1] neg_hi:[0,1]
	v_max_f32_e32 v228, 0, v228
	v_max_f32_e32 v229, 0, v229
	v_sqrt_f32_e32 v228, v228
	v_sqrt_f32_e32 v229, v229
	ds_write_b32 v175, v226 offset:7328
	ds_write_b32 v175, v227 offset:7600
	v_pk_mul_f32 v[228:229], v[126:127], v[228:229]
	s_waitcnt lgkmcnt(2)
	v_pk_mul_f32 v[228:229], v[230:231], v[228:229]
	ds_write2_b32 v233, v228, v229 offset0:168 offset1:236
	ds_read2_b32 v[230:231], v233 offset0:48 offset1:116
	v_pk_add_f32 v[124:125], v[136:137], v[192:193] op_sel_hi:[1,0]
	v_add_f32_e64 v126, v140, v191
	v_add_f32_e64 v127, v141, v191
	v_pk_mul_f32 v[124:125], v[124:125], v[232:233] op_sel_hi:[1,0]
	v_pk_mul_f32 v[126:127], v[126:127], v[232:233] op_sel_hi:[1,0]
	v_exp_f32_e32 v124, v124
	v_exp_f32_e32 v125, v125
	v_exp_f32_e32 v126, v126
	v_exp_f32_e32 v127, v127
	v_pk_add_f32 v[124:125], v[124:125], v[168:169] op_sel_hi:[1,0]
	v_pk_add_f32 v[126:127], v[126:127], v[168:169] op_sel_hi:[1,0]
	v_rcp_f32_e32 v124, v124
	v_rcp_f32_e32 v125, v125
	v_rcp_f32_e32 v126, v126
	v_rcp_f32_e32 v127, v127
	v_mul_f32_e64 v170, v124, v221
	v_mul_f32_e64 v171, v125, v221
	v_mul_f32_e32 v226, 0x3fb8aa3b, v170
	v_mul_f32_e32 v227, 0x3fb8aa3b, v171
	v_pk_add_f32 v[170:171], v[170:171], v[170:171]
	v_exp_f32_e32 v226, v226
	v_exp_f32_e32 v227, v227
	v_pk_fma_f32 v[228:229], v[170:171], s[0:1], v[198:199] op_sel_hi:[1,1,0]
	v_pk_fma_f32 v[228:229], v[170:171], v[228:229], s[80:81]
	v_pk_fma_f32 v[228:229], v[170:171], v[228:229], s[82:83]
	v_pk_fma_f32 v[228:229], v[170:171], v[228:229], s[84:85]
	v_fmaak_f32 v228, v170, v228, 0x3e2aaaab
	v_fmaak_f32 v229, v171, v229, 0x3e2aaaab
	v_fma_f32 v228, v170, v228, 0.5
	v_fma_f32 v229, v171, v229, 0.5
	v_pk_fma_f32 v[228:229], v[170:171], v[228:229], v[168:169] op_sel_hi:[1,1,0]
	v_pk_mul_f32 v[228:229], v[170:171], v[228:229] neg_lo:[0,1] neg_hi:[0,1]
	v_max_f32_e32 v228, 0, v228
	v_max_f32_e32 v229, 0, v229
	v_sqrt_f32_e32 v228, v228
	v_sqrt_f32_e32 v229, v229
	ds_write_b32 v175, v226 offset:6848
	ds_write_b32 v175, v227 offset:7120
	v_pk_mul_f32 v[228:229], v[126:127], v[228:229]
	s_waitcnt lgkmcnt(2)
	v_pk_mul_f32 v[228:229], v[230:231], v[228:229]
	ds_write2_b32 v233, v228, v229 offset0:48 offset1:116
	ds_read2_b32 v[230:231], v233 offset0:184 offset1:252
	v_pk_add_f32 v[124:125], v[138:139], v[192:193] op_sel_hi:[1,0]
	v_add_f32_e64 v126, v142, v191
	v_add_f32_e64 v127, v143, v191
	v_pk_mul_f32 v[124:125], v[124:125], v[232:233] op_sel_hi:[1,0]
	v_pk_mul_f32 v[126:127], v[126:127], v[232:233] op_sel_hi:[1,0]
	v_exp_f32_e32 v124, v124
	v_exp_f32_e32 v125, v125
	v_exp_f32_e32 v126, v126
	v_exp_f32_e32 v127, v127
	v_pk_add_f32 v[124:125], v[124:125], v[168:169] op_sel_hi:[1,0]
	v_pk_add_f32 v[126:127], v[126:127], v[168:169] op_sel_hi:[1,0]
	v_rcp_f32_e32 v124, v124
	v_rcp_f32_e32 v125, v125
	v_rcp_f32_e32 v126, v126
	v_rcp_f32_e32 v127, v127
	v_mul_f32_e64 v170, v124, v221
	v_mul_f32_e64 v171, v125, v221
	v_mul_f32_e32 v226, 0x3fb8aa3b, v170
	v_mul_f32_e32 v227, 0x3fb8aa3b, v171
	v_pk_add_f32 v[170:171], v[170:171], v[170:171]
	v_exp_f32_e32 v226, v226
	v_exp_f32_e32 v227, v227
	v_pk_fma_f32 v[228:229], v[170:171], s[0:1], v[198:199] op_sel_hi:[1,1,0]
	v_pk_fma_f32 v[228:229], v[170:171], v[228:229], s[80:81]
	v_pk_fma_f32 v[228:229], v[170:171], v[228:229], s[82:83]
	v_pk_fma_f32 v[228:229], v[170:171], v[228:229], s[84:85]
	v_fmaak_f32 v228, v170, v228, 0x3e2aaaab
	v_fmaak_f32 v229, v171, v229, 0x3e2aaaab
	v_fma_f32 v228, v170, v228, 0.5
	v_fma_f32 v229, v171, v229, 0.5
	v_pk_fma_f32 v[228:229], v[170:171], v[228:229], v[168:169] op_sel_hi:[1,1,0]
	v_pk_mul_f32 v[228:229], v[170:171], v[228:229] neg_lo:[0,1] neg_hi:[0,1]
	v_max_f32_e32 v228, 0, v228
	v_max_f32_e32 v229, 0, v229
	v_sqrt_f32_e32 v228, v228
	v_sqrt_f32_e32 v229, v229
	ds_write_b32 v175, v226 offset:7392
	ds_write_b32 v175, v227 offset:7664
	v_pk_mul_f32 v[228:229], v[126:127], v[228:229]
	s_waitcnt lgkmcnt(2)
	v_pk_mul_f32 v[228:229], v[230:231], v[228:229]
	ds_write2_b32 v233, v228, v229 offset0:184 offset1:252
	v_add_u32_e32 v126, 0x1c00, v174
	s_waitcnt lgkmcnt(0)
	v_add_u32_e32 v120, 0x1800, v174
	v_add_u32_e32 v122, 0x800, v174
	ds_read2_b32 v[120:121], v120 offset0:128 offset1:196
	ds_read2_b32 v[122:123], v122 offset0:64 offset1:132
	v_add_u32_e32 v124, 0xa00, v174
	ds_read2_b32 v[124:125], v124 offset0:72 offset1:140
	s_waitcnt lgkmcnt(1)
	v_fma_f32 v122, v164, v120, v122
	v_mul_f32_e32 v120, v169, v120
	v_fmac_f32_e32 v123, v122, v121
	v_mul_f32_e32 v122, v120, v121
	ds_read2_b32 v[120:121], v126 offset0:8 offset1:76
	s_waitcnt lgkmcnt(0)
	v_fma_f32 v123, v123, v120, v124
	v_mul_f32_e32 v120, v122, v120
	v_add_u32_e32 v122, 0xc00, v174
	v_fmac_f32_e32 v125, v123, v121
	v_mul_f32_e32 v124, v120, v121
	ds_read2_b32 v[120:121], v126 offset0:144 offset1:212
	ds_read2_b32 v[122:123], v122 offset0:80 offset1:148
	s_waitcnt lgkmcnt(0)
	v_fma_f32 v122, v125, v120, v122
	v_mul_f32_e32 v120, v124, v120
	v_fmac_f32_e32 v123, v122, v121
	v_mul_f32_e32 v121, v120, v121
	v_add_u32_e32 v120, 0x2000, v174
	v_add_u32_e32 v122, 0xe00, v174
	ds_read2_b32 v[124:125], v120 offset0:24 offset1:92
	ds_read2_b32 v[126:127], v122 offset0:88 offset1:156
	s_waitcnt lgkmcnt(1)
	v_mov_b32_e32 v139, v124
	s_waitcnt lgkmcnt(0)
	v_fma_f32 v122, v123, v124, v126
	v_fmac_f32_e32 v127, v122, v125
	ds_read2_b32 v[122:123], v120 offset0:160 offset1:228
	v_add_u32_e32 v120, 0x1000, v174
	ds_read2_b32 v[128:129], v120 offset0:96 offset1:164
	s_waitcnt lgkmcnt(0)
	v_fma_f32 v120, v127, v122, v128
	v_fmac_f32_e32 v129, v120, v123
	v_add_u32_e32 v120, 0x2400, v174
	v_add_u32_e32 v128, 0x1200, v174
	ds_read2_b32 v[126:127], v120 offset0:40 offset1:108
	ds_read2_b32 v[130:131], v128 offset0:104 offset1:172
	s_waitcnt lgkmcnt(1)
	v_mov_b32_e32 v138, v127
	s_waitcnt lgkmcnt(0)
	v_fmac_f32_e32 v130, v129, v126
	ds_read2_b32 v[128:129], v120 offset0:176 offset1:244
	v_add_u32_e32 v120, 0x1400, v174
	ds_read2_b32 v[132:133], v120 offset0:112 offset1:180
	v_add_u32_e32 v120, 0x2800, v174
	ds_read2_b32 v[134:135], v120 offset0:56 offset1:124
	v_add_u32_e32 v120, 0x1600, v174
	ds_read2_b32 v[136:137], v120 offset0:120 offset1:188
	v_mov_b32_e32 v120, v130
	v_pk_mul_f32 v[140:141], v[120:121], v[138:139]
	v_mov_b32_e32 v130, v131
	v_mov_b32_e32 v124, v131
	v_pk_fma_f32 v[120:121], v[120:121], v[138:139], v[130:131]
	v_pk_mul_f32 v[124:125], v[140:141], v[124:125]
	s_waitcnt lgkmcnt(3)
	v_mov_b32_e32 v130, v128
	v_mov_b32_e32 v131, v122
	v_mov_b32_e32 v121, v125
	v_pk_mul_f32 v[124:125], v[124:125], v[130:131]
	s_waitcnt lgkmcnt(2)
	v_mov_b32_e32 v122, v132
	v_pk_fma_f32 v[120:121], v[120:121], v[130:131], v[132:133]
	v_pk_mul_f32 v[122:123], v[124:125], v[122:123]
	v_mov_b32_e32 v130, v133
	v_mov_b32_e32 v121, v123
	v_mov_b32_e32 v122, v129
	v_mov_b32_e32 v123, v126
	v_pk_mul_f32 v[124:125], v[120:121], v[122:123]
	v_mov_b32_e32 v126, v133
	v_pk_fma_f32 v[120:121], v[120:121], v[122:123], v[130:131]
	v_pk_mul_f32 v[122:123], v[124:125], v[126:127]
	s_waitcnt lgkmcnt(1)
	v_mov_b32_e32 v124, v134
	v_mov_b32_e32 v125, v128
	v_mov_b32_e32 v121, v123
	v_pk_mul_f32 v[122:123], v[122:123], v[124:125]
	s_waitcnt lgkmcnt(0)
	v_mov_b32_e32 v128, v136
	v_pk_fma_f32 v[120:121], v[120:121], v[124:125], v[136:137]
	v_pk_mul_f32 v[122:123], v[122:123], v[128:129]
	s_waitcnt lgkmcnt(0)
	s_nop 0
	v_mov_b32_e32 v121, v123
	v_mov_b32_e32 v122, v135
	v_mov_b32_e32 v123, v134
	v_pk_mul_f32 v[124:125], v[120:121], v[122:123]
	v_mov_b32_e32 v134, v137
	v_pk_fma_f32 v[164:165], v[120:121], v[122:123], v[134:135]
	v_pk_mul_f32 v[168:169], v[124:125], v[134:135]
	s_cbranch_scc0 .LBB0_194
